# loop-edge rotation extended to all 7 GEMM K-loops (in-proj, out-proj, up-proj added) on top of conv fill batching and setprio removal
# baseline (speedup 1.0000x reference)
; #define PG8_STAGE(bufoff, gbase, voff) do { _Pragma("unroll") for (int _i = 0; _i < 2; ++_i) \
;         __builtin_amdgcn_global_load_lds((const unsigned*)((const char*)(gbase) + (voff)[_i]), (PG8_LAS unsigned*)(lds + (bufoff) + ldsw + _i * 8192), 16, 0, 0); } while (0)
; #define PG8_LDA(dst, b, h) do { _Pragma("unroll") for (int m = 0; m < 4; ++m) _Pragma("unroll") for (int k = 0; k < 2; ++k) dst[m][k] = *(const PG8_LAS bf16x8*)(lds + PG8_SA(b, h) + aoff + m * 2048 + k * 1024); } while (0)
; #define PG8_LDB(dst, b, h) do { _Pragma("unroll") for (int n = 0; n < 2; ++n) _Pragma("unroll") for (int k = 0; k < 2; ++k) dst[n][k] = *(const PG8_LAS bf16x8*)(lds + PG8_SB(b, h) + boff + n * 2048 + k * 1024); } while (0)
; #define PG8_MMA(ai, bj, At, Bt) do { __builtin_amdgcn_s_setprio(1); _Pragma("unroll") for (int m = 0; m < 4; ++m) _Pragma("unroll") for (int n = 0; n < 2; ++n) _Pragma("unroll") for (int k = 0; k < 2; ++k) \
;         acc[ai][bj][m][n] = __builtin_amdgcn_mfma_f32_16x16x32_bf16(Bt[n][k], At[m][k], acc[ai][bj][m][n], 0, 0, 0); __builtin_amdgcn_s_setprio(0); } while (0)
; #define PG8_WAIT_V(n) asm volatile("s_waitcnt vmcnt(" #n ")" ::: "memory")
; #define PG8_BAR __builtin_amdgcn_s_barrier()
; template <class Epi, class Sched, bool ALIGN_EPI = false, bool SP2 = false>
; __device__ __forceinline__ void gemm_phase(PG8_LAS unsigned char* lds, const Gemm g, const Sched& S, const Epi& E) {
;     ...
;         for (int t = 0; t < nt; t += 2) {
;             const bool last = (t == nt - 2);
;             const char* a1 = cA + (size_t)(t + 1) * kstep;
;             const char* a2 = last ? nA : cA + (size_t)(t + 2) * kstep; const char* b2 = last ? nB : cB + (size_t)(t + 2) * kstep;
;             const char* a3 = a2 + kstep; const char* b3 = b2 + kstep;
;             if (last && has_next) S.a_ready(nxt);
;             if constexpr (SP2) {
;             PG8_LDB(B0, 0, 0); PG8_LDB(B1, 0, 1); PG8_SCHED; PG8_LDA(At, 0, 0); PG8_STAGE(PG8_SA(1, 1), a1 + hstepA, voffA);
;             PG8_WAIT_V(8); PG8_WAIT_L(0); PG8_BAR; PG8_MMA(0, 0, At, B0); PG8_MMA(0, 1, At, B1); PG8_BAR; PG8_SCHED;
;             PG8_LDA(At, 0, 1); PG8_STAGE(PG8_SB(0, 0), b2, voffB); PG8_STAGE(PG8_SB(0, 1), b2 + hstepB, voffB); PG8_STAGE(PG8_SA(0, 0), a2, voffA);
;             PG8_WAIT_V(8); PG8_WAIT_L(0); PG8_BAR; PG8_MMA(1, 0, At, B0); PG8_MMA(1, 1, At, B1); PG8_BAR; PG8_SCHED;
.Lgk_168:
	ds_read_b128 v[164:167], v130
	ds_read_b128 v[168:171], v130 offset:1024
	ds_read_b128 v[186:189], v130 offset:2048
	ds_read_b128 v[190:193], v130 offset:3072
	v_add_u32_e32 v130, s81, v161
	ds_read_b128 v[198:201], v130
	ds_read_b128 v[202:205], v130 offset:1024
	ds_read_b128 v[206:209], v130 offset:2048
	ds_read_b128 v[210:213], v130 offset:3072
	v_lshl_add_u64 v[130:131], s[48:49], 0, v[156:157]
	s_add_i32 m0, s9, 0xc000
	ds_read_b128 v[214:217], v163
	ds_read_b128 v[218:221], v163 offset:1024
	ds_read_b128 v[222:225], v163 offset:2048
	ds_read_b128 v[226:229], v163 offset:3072
	ds_read_b128 v[230:233], v163 offset:4096
	ds_read_b128 v[234:237], v163 offset:5120
	ds_read_b128 v[238:241], v163 offset:6144
	ds_read_b128 v[242:245], v163 offset:7168
	global_load_lds_dwordx4 v[130:131], off
	v_lshl_add_u64 v[130:131], s[48:49], 0, v[158:159]
	s_add_i32 m0, s9, 0xe000
	s_nop 0
	global_load_lds_dwordx4 v[130:131], off
	s_waitcnt vmcnt(8)
	s_waitcnt lgkmcnt(0)
	s_barrier
	s_waitcnt lgkmcnt(0)
	v_mfma_f32_16x16x32_bf16 v[126:129], v[164:167], v[214:217], v[126:129]
	v_mfma_f32_16x16x32_bf16 v[122:125], v[186:189], v[214:217], v[122:125]
	v_mfma_f32_16x16x32_bf16 v[118:121], v[164:167], v[222:225], v[118:121]
	v_mfma_f32_16x16x32_bf16 v[114:117], v[186:189], v[222:225], v[114:117]
	v_mfma_f32_16x16x32_bf16 v[102:105], v[164:167], v[230:233], v[102:105]
	v_mfma_f32_16x16x32_bf16 v[98:101], v[186:189], v[230:233], v[98:101]
	v_mfma_f32_16x16x32_bf16 v[86:89], v[164:167], v[238:241], v[86:89]
	v_mfma_f32_16x16x32_bf16 v[82:85], v[186:189], v[238:241], v[82:85]
	v_mfma_f32_16x16x32_bf16 v[126:129], v[168:171], v[218:221], v[126:129]
	v_mfma_f32_16x16x32_bf16 v[122:125], v[190:193], v[218:221], v[122:125]
	v_mfma_f32_16x16x32_bf16 v[118:121], v[168:171], v[226:229], v[118:121]
	v_mfma_f32_16x16x32_bf16 v[114:117], v[190:193], v[226:229], v[114:117]
	v_mfma_f32_16x16x32_bf16 v[102:105], v[168:171], v[234:237], v[102:105]
	v_mfma_f32_16x16x32_bf16 v[98:101], v[190:193], v[234:237], v[98:101]
	v_mfma_f32_16x16x32_bf16 v[86:89], v[168:171], v[242:245], v[86:89]
	v_mfma_f32_16x16x32_bf16 v[82:85], v[190:193], v[242:245], v[82:85]
	v_mfma_f32_16x16x32_bf16 v[110:113], v[198:201], v[214:217], v[110:113]
	v_mfma_f32_16x16x32_bf16 v[106:109], v[206:209], v[214:217], v[106:109]
	v_mfma_f32_16x16x32_bf16 v[94:97], v[198:201], v[222:225], v[94:97]
	v_mfma_f32_16x16x32_bf16 v[90:93], v[206:209], v[222:225], v[90:93]
	v_mfma_f32_16x16x32_bf16 v[78:81], v[198:201], v[230:233], v[78:81]
	v_mfma_f32_16x16x32_bf16 v[74:77], v[206:209], v[230:233], v[74:77]
	v_mfma_f32_16x16x32_bf16 v[70:73], v[198:201], v[238:241], v[70:73]
	v_mfma_f32_16x16x32_bf16 v[66:69], v[206:209], v[238:241], v[66:69]
	v_mfma_f32_16x16x32_bf16 v[110:113], v[202:205], v[218:221], v[110:113]
	v_mfma_f32_16x16x32_bf16 v[106:109], v[210:213], v[218:221], v[106:109]
	v_mfma_f32_16x16x32_bf16 v[94:97], v[202:205], v[226:229], v[94:97]
	v_mfma_f32_16x16x32_bf16 v[90:93], v[210:213], v[226:229], v[90:93]
	v_mfma_f32_16x16x32_bf16 v[78:81], v[202:205], v[234:237], v[78:81]
	v_mfma_f32_16x16x32_bf16 v[74:77], v[210:213], v[234:237], v[74:77]
	v_mfma_f32_16x16x32_bf16 v[70:73], v[202:205], v[242:245], v[70:73]
	v_mfma_f32_16x16x32_bf16 v[66:69], v[210:213], v[242:245], v[66:69]
	s_barrier
	s_add_i32 s10, s69, s8
	v_lshl_add_u64 v[130:131], s[50:51], 0, v[0:1]
	s_mov_b32 m0, s10
	ds_read_b128 v[214:217], v163 offset:16384
	ds_read_b128 v[218:221], v163 offset:17408
	ds_read_b128 v[222:225], v163 offset:18432
	ds_read_b128 v[226:229], v163 offset:19456
	ds_read_b128 v[230:233], v163 offset:20480
	ds_read_b128 v[234:237], v163 offset:21504
	ds_read_b128 v[238:241], v163 offset:22528
	ds_read_b128 v[242:245], v163 offset:23552
	global_load_lds_dwordx4 v[130:131], off
	s_add_i32 m0, s10, 0x2000
	s_add_u32 s10, s50, 0x40000
	v_lshl_add_u64 v[132:133], s[50:51], 0, v[154:155]
	s_addc_u32 s11, s51, 0
	s_add_i32 s69, s81, s8
	global_load_lds_dwordx4 v[132:133], off
	v_lshl_add_u64 v[172:173], s[10:11], 0, v[0:1]
	s_mov_b32 m0, s69
	v_lshl_add_u64 v[246:247], s[52:53], 0, v[152:153]
	global_load_lds_dwordx4 v[172:173], off
	v_lshl_add_u64 v[172:173], s[10:11], 0, v[154:155]
	s_add_i32 m0, s69, 0x2000
	s_nop 0
	global_load_lds_dwordx4 v[172:173], off
	v_lshl_add_u64 v[172:173], s[52:53], 0, v[150:151]
	s_mov_b32 m0, s9
	s_nop 0
	global_load_lds_dwordx4 v[172:173], off
	s_mov_b32 m0, s30
	s_nop 0
	global_load_lds_dwordx4 v[246:247], off
	s_waitcnt vmcnt(8)
	s_waitcnt lgkmcnt(0)
	s_barrier
	s_waitcnt lgkmcnt(0)
	v_mfma_f32_16x16x32_bf16 v[62:65], v[164:167], v[214:217], v[62:65]
	v_mfma_f32_16x16x32_bf16 v[58:61], v[186:189], v[214:217], v[58:61]
	v_mfma_f32_16x16x32_bf16 v[54:57], v[164:167], v[222:225], v[54:57]
	v_mfma_f32_16x16x32_bf16 v[50:53], v[186:189], v[222:225], v[50:53]
	v_mfma_f32_16x16x32_bf16 v[38:41], v[164:167], v[230:233], v[38:41]
	v_mfma_f32_16x16x32_bf16 v[34:37], v[186:189], v[230:233], v[34:37]
	v_mfma_f32_16x16x32_bf16 v[22:25], v[164:167], v[238:241], v[22:25]
	v_mfma_f32_16x16x32_bf16 v[18:21], v[186:189], v[238:241], v[18:21]
	v_mfma_f32_16x16x32_bf16 v[62:65], v[168:171], v[218:221], v[62:65]
	v_mfma_f32_16x16x32_bf16 v[58:61], v[190:193], v[218:221], v[58:61]
	v_mfma_f32_16x16x32_bf16 v[54:57], v[168:171], v[226:229], v[54:57]
	v_mfma_f32_16x16x32_bf16 v[50:53], v[190:193], v[226:229], v[50:53]
	v_mfma_f32_16x16x32_bf16 v[38:41], v[168:171], v[234:237], v[38:41]
	v_mfma_f32_16x16x32_bf16 v[34:37], v[190:193], v[234:237], v[34:37]
	v_mfma_f32_16x16x32_bf16 v[22:25], v[168:171], v[242:245], v[22:25]
	v_mfma_f32_16x16x32_bf16 v[18:21], v[190:193], v[242:245], v[18:21]
	v_mfma_f32_16x16x32_bf16 v[46:49], v[198:201], v[214:217], v[46:49]
	v_mfma_f32_16x16x32_bf16 v[42:45], v[206:209], v[214:217], v[42:45]
	v_mfma_f32_16x16x32_bf16 v[30:33], v[198:201], v[222:225], v[30:33]
	v_mfma_f32_16x16x32_bf16 v[26:29], v[206:209], v[222:225], v[26:29]
	v_mfma_f32_16x16x32_bf16 v[14:17], v[198:201], v[230:233], v[14:17]
	v_mfma_f32_16x16x32_bf16 v[10:13], v[206:209], v[230:233], v[10:13]
	v_mfma_f32_16x16x32_bf16 v[6:9], v[198:201], v[238:241], v[6:9]
	v_mfma_f32_16x16x32_bf16 v[2:5], v[206:209], v[238:241], v[2:5]
	v_mfma_f32_16x16x32_bf16 v[46:49], v[202:205], v[218:221], v[46:49]
	v_mfma_f32_16x16x32_bf16 v[42:45], v[210:213], v[218:221], v[42:45]
	v_mfma_f32_16x16x32_bf16 v[30:33], v[202:205], v[226:229], v[30:33]
	v_mfma_f32_16x16x32_bf16 v[26:29], v[210:213], v[226:229], v[26:29]
	v_mfma_f32_16x16x32_bf16 v[14:17], v[202:205], v[234:237], v[14:17]
	v_mfma_f32_16x16x32_bf16 v[10:13], v[210:213], v[234:237], v[10:13]
	v_mfma_f32_16x16x32_bf16 v[6:9], v[202:205], v[242:245], v[6:9]
	v_mfma_f32_16x16x32_bf16 v[2:5], v[210:213], v[242:245], v[2:5]
	s_barrier
; #define PG8_STAGE(bufoff, gbase, voff) do { _Pragma("unroll") for (int _i = 0; _i < 2; ++_i) \
;         __builtin_amdgcn_global_load_lds((const unsigned*)((const char*)(gbase) + (voff)[_i]), (PG8_LAS unsigned*)(lds + (bufoff) + ldsw + _i * 8192), 16, 0, 0); } while (0)
; #define PG8_LDA(dst, b, h) do { _Pragma("unroll") for (int m = 0; m < 4; ++m) _Pragma("unroll") for (int k = 0; k < 2; ++k) dst[m][k] = *(const PG8_LAS bf16x8*)(lds + PG8_SA(b, h) + aoff + m * 2048 + k * 1024); } while (0)
; #define PG8_LDB(dst, b, h) do { _Pragma("unroll") for (int n = 0; n < 2; ++n) _Pragma("unroll") for (int k = 0; k < 2; ++k) dst[n][k] = *(const PG8_LAS bf16x8*)(lds + PG8_SB(b, h) + boff + n * 2048 + k * 1024); } while (0)
; #define PG8_MMA(ai, bj, At, Bt) do { __builtin_amdgcn_s_setprio(1); _Pragma("unroll") for (int m = 0; m < 4; ++m) _Pragma("unroll") for (int n = 0; n < 2; ++n) _Pragma("unroll") for (int k = 0; k < 2; ++k) \
;         acc[ai][bj][m][n] = __builtin_amdgcn_mfma_f32_16x16x32_bf16(Bt[n][k], At[m][k], acc[ai][bj][m][n], 0, 0, 0); __builtin_amdgcn_s_setprio(0); } while (0)
; #define PG8_WAIT_V(n) asm volatile("s_waitcnt vmcnt(" #n ")" ::: "memory")
; #define PG8_WAIT_L(n) asm volatile("s_waitcnt lgkmcnt(" #n ")" ::: "memory")
; #define PG8_BAR __builtin_amdgcn_s_barrier()
; #define PG8_SCHED __builtin_amdgcn_sched_barrier(0)
; template <class Epi, class Sched, bool ALIGN_EPI = false, bool SP2 = false>
; __device__ __forceinline__ void gemm_phase(PG8_LAS unsigned char* lds, const Gemm g, const Sched& S, const Epi& E) {
;     ...
;             PG8_LDB(B0, 1, 0); PG8_LDB(B1, 1, 1); PG8_SCHED; PG8_LDA(At, 1, 0); PG8_STAGE(PG8_SA(0, 1), a2 + hstepA, voffA);
;             PG8_WAIT_V(8); PG8_WAIT_L(0); PG8_BAR; PG8_MMA(0, 0, At, B0); PG8_MMA(0, 1, At, B1); PG8_BAR; PG8_SCHED;
	s_add_i32 s69, 0, 0x18000
	s_add_i32 s81, 0, 0x1c000
	v_add_u32_e32 v190, s69, v161
	v_add_u32_e32 v210, s81, v161
	ds_read_b128 v[164:167], v190
	ds_read_b128 v[168:171], v190 offset:1024
	ds_read_b128 v[186:189], v190 offset:2048
	ds_read_b128 v[190:193], v190 offset:3072
	ds_read_b128 v[198:201], v210
	ds_read_b128 v[202:205], v210 offset:1024
	ds_read_b128 v[206:209], v210 offset:2048
	ds_read_b128 v[210:213], v210 offset:3072
	s_add_u32 s10, s52, 0x40000
	s_addc_u32 s11, s53, 0
	s_mov_b32 m0, s31
	v_lshl_add_u64 v[248:249], s[10:11], 0, v[150:151]
	ds_read_b128 v[214:217], v163 offset:32768
	ds_read_b128 v[218:221], v163 offset:33792
	ds_read_b128 v[222:225], v163 offset:34816
	ds_read_b128 v[226:229], v163 offset:35840
	ds_read_b128 v[230:233], v163 offset:36864
	ds_read_b128 v[234:237], v163 offset:37888
	ds_read_b128 v[238:241], v163 offset:38912
	ds_read_b128 v[242:245], v163 offset:39936
	global_load_lds_dwordx4 v[248:249], off
	v_lshl_add_u64 v[248:249], s[10:11], 0, v[152:153]
	s_mov_b32 m0, s34
	s_nop 0
	global_load_lds_dwordx4 v[248:249], off
	s_waitcnt vmcnt(8)
	s_waitcnt lgkmcnt(0)
	s_barrier
	s_waitcnt lgkmcnt(0)
	v_mfma_f32_16x16x32_bf16 v[126:129], v[164:167], v[214:217], v[126:129]
	v_mfma_f32_16x16x32_bf16 v[122:125], v[186:189], v[214:217], v[122:125]
	v_mfma_f32_16x16x32_bf16 v[118:121], v[164:167], v[222:225], v[118:121]
	v_mfma_f32_16x16x32_bf16 v[114:117], v[186:189], v[222:225], v[114:117]
	v_mfma_f32_16x16x32_bf16 v[102:105], v[164:167], v[230:233], v[102:105]
	v_mfma_f32_16x16x32_bf16 v[98:101], v[186:189], v[230:233], v[98:101]
	v_mfma_f32_16x16x32_bf16 v[86:89], v[164:167], v[238:241], v[86:89]
	v_mfma_f32_16x16x32_bf16 v[82:85], v[186:189], v[238:241], v[82:85]
	v_mfma_f32_16x16x32_bf16 v[126:129], v[168:171], v[218:221], v[126:129]
	v_mfma_f32_16x16x32_bf16 v[122:125], v[190:193], v[218:221], v[122:125]
	v_mfma_f32_16x16x32_bf16 v[118:121], v[168:171], v[226:229], v[118:121]
	v_mfma_f32_16x16x32_bf16 v[114:117], v[190:193], v[226:229], v[114:117]
	v_mfma_f32_16x16x32_bf16 v[102:105], v[168:171], v[234:237], v[102:105]
	v_mfma_f32_16x16x32_bf16 v[98:101], v[190:193], v[234:237], v[98:101]
	v_mfma_f32_16x16x32_bf16 v[86:89], v[168:171], v[242:245], v[86:89]
	v_mfma_f32_16x16x32_bf16 v[82:85], v[190:193], v[242:245], v[82:85]
	v_mfma_f32_16x16x32_bf16 v[110:113], v[198:201], v[214:217], v[110:113]
	v_mfma_f32_16x16x32_bf16 v[106:109], v[206:209], v[214:217], v[106:109]
	v_mfma_f32_16x16x32_bf16 v[94:97], v[198:201], v[222:225], v[94:97]
	v_mfma_f32_16x16x32_bf16 v[90:93], v[206:209], v[222:225], v[90:93]
	v_mfma_f32_16x16x32_bf16 v[78:81], v[198:201], v[230:233], v[78:81]
	v_mfma_f32_16x16x32_bf16 v[74:77], v[206:209], v[230:233], v[74:77]
	v_mfma_f32_16x16x32_bf16 v[70:73], v[198:201], v[238:241], v[70:73]
	v_mfma_f32_16x16x32_bf16 v[66:69], v[206:209], v[238:241], v[66:69]
	v_mfma_f32_16x16x32_bf16 v[110:113], v[202:205], v[218:221], v[110:113]
	v_mfma_f32_16x16x32_bf16 v[106:109], v[210:213], v[218:221], v[106:109]
	v_mfma_f32_16x16x32_bf16 v[94:97], v[202:205], v[226:229], v[94:97]
	v_mfma_f32_16x16x32_bf16 v[90:93], v[210:213], v[226:229], v[90:93]
	v_mfma_f32_16x16x32_bf16 v[78:81], v[202:205], v[234:237], v[78:81]
	v_mfma_f32_16x16x32_bf16 v[74:77], v[210:213], v[234:237], v[74:77]
	v_mfma_f32_16x16x32_bf16 v[70:73], v[202:205], v[242:245], v[70:73]
	v_mfma_f32_16x16x32_bf16 v[66:69], v[210:213], v[242:245], v[66:69]
	s_barrier
; #define PG8_STAGE(bufoff, gbase, voff) do { _Pragma("unroll") for (int _i = 0; _i < 2; ++_i) \
;         __builtin_amdgcn_global_load_lds((const unsigned*)((const char*)(gbase) + (voff)[_i]), (PG8_LAS unsigned*)(lds + (bufoff) + ldsw + _i * 8192), 16, 0, 0); } while (0)
; #define PG8_LDA(dst, b, h) do { _Pragma("unroll") for (int m = 0; m < 4; ++m) _Pragma("unroll") for (int k = 0; k < 2; ++k) dst[m][k] = *(const PG8_LAS bf16x8*)(lds + PG8_SA(b, h) + aoff + m * 2048 + k * 1024); } while (0)
; #define PG8_MMA(ai, bj, At, Bt) do { __builtin_amdgcn_s_setprio(1); _Pragma("unroll") for (int m = 0; m < 4; ++m) _Pragma("unroll") for (int n = 0; n < 2; ++n) _Pragma("unroll") for (int k = 0; k < 2; ++k) \
;         acc[ai][bj][m][n] = __builtin_amdgcn_mfma_f32_16x16x32_bf16(Bt[n][k], At[m][k], acc[ai][bj][m][n], 0, 0, 0); __builtin_amdgcn_s_setprio(0); } while (0)
; #define PG8_WAIT_V(n) asm volatile("s_waitcnt vmcnt(" #n ")" ::: "memory")
; #define PG8_WAIT_L(n) asm volatile("s_waitcnt lgkmcnt(" #n ")" ::: "memory")
; #define PG8_BAR __builtin_amdgcn_s_barrier()
; #define PG8_SCHED __builtin_amdgcn_sched_barrier(0)
; template <class Epi, class Sched, bool ALIGN_EPI = false, bool SP2 = false>
; __device__ __forceinline__ void gemm_phase(PG8_LAS unsigned char* lds, const Gemm g, const Sched& S, const Epi& E) {
;     ...
;         for (int t = 0; t < nt; t += 2) {
;             const bool last = (t == nt - 2);
;             const char* a1 = cA + (size_t)(t + 1) * kstep;
;             const char* a2 = last ? nA : cA + (size_t)(t + 2) * kstep; const char* b2 = last ? nB : cB + (size_t)(t + 2) * kstep;
;             const char* a3 = a2 + kstep; const char* b3 = b2 + kstep;
;     ...
;             PG8_LDA(At, 1, 1); PG8_STAGE(PG8_SB(1, 0), b3, voffB); PG8_STAGE(PG8_SB(1, 1), b3 + hstepB, voffB); PG8_STAGE(PG8_SA(1, 0), a3, voffA);
;             PG8_WAIT_V(8); PG8_WAIT_L(0); PG8_BAR; PG8_MMA(1, 0, At, B0); PG8_MMA(1, 1, At, B1); PG8_BAR; PG8_SCHED;
	s_add_i32 s10, s69, s8
	v_lshl_add_u64 v[130:131], v[130:131], 0, s[2:3]
	s_mov_b32 m0, s10
	ds_read_b128 v[214:217], v163 offset:49152
	ds_read_b128 v[218:221], v163 offset:50176
	ds_read_b128 v[222:225], v163 offset:51200
	ds_read_b128 v[226:229], v163 offset:52224
	ds_read_b128 v[230:233], v163 offset:53248
	ds_read_b128 v[234:237], v163 offset:54272
	ds_read_b128 v[238:241], v163 offset:55296
	ds_read_b128 v[242:245], v163 offset:56320
	global_load_lds_dwordx4 v[130:131], off
	s_add_i32 m0, s10, 0x2000
	s_add_u32 s10, s50, 0x40080
	v_lshl_add_u64 v[130:131], v[132:133], 0, s[2:3]
	s_addc_u32 s11, s51, 0
	s_add_i32 s50, s81, s8
	global_load_lds_dwordx4 v[130:131], off
	v_lshl_add_u64 v[130:131], s[10:11], 0, v[0:1]
	s_mov_b32 m0, s50
	s_nop 0
	global_load_lds_dwordx4 v[130:131], off
	v_lshl_add_u64 v[130:131], s[10:11], 0, v[154:155]
	s_add_i32 m0, s50, 0x2000
	s_nop 0
	global_load_lds_dwordx4 v[130:131], off
	v_lshl_add_u64 v[130:131], v[172:173], 0, s[2:3]
	s_mov_b32 m0, s35
	s_nop 0
	global_load_lds_dwordx4 v[130:131], off
	v_lshl_add_u64 v[130:131], v[246:247], 0, s[2:3]
	s_mov_b32 m0, s39
	s_nop 0
	global_load_lds_dwordx4 v[130:131], off
	s_waitcnt vmcnt(8)
	s_waitcnt lgkmcnt(0)
	s_barrier
	s_waitcnt lgkmcnt(0)
	v_mfma_f32_16x16x32_bf16 v[62:65], v[164:167], v[214:217], v[62:65]
	v_mfma_f32_16x16x32_bf16 v[58:61], v[186:189], v[214:217], v[58:61]
	s_add_i32 s68, s68, 2
	v_mfma_f32_16x16x32_bf16 v[54:57], v[164:167], v[222:225], v[54:57]
	s_add_u32 s48, s48, 0x100
	v_mfma_f32_16x16x32_bf16 v[50:53], v[186:189], v[222:225], v[50:53]
	s_addc_u32 s49, s49, 0
	v_mfma_f32_16x16x32_bf16 v[38:41], v[164:167], v[230:233], v[38:41]
	s_add_u32 s62, s62, 0x100
	v_mfma_f32_16x16x32_bf16 v[34:37], v[186:189], v[230:233], v[34:37]
	s_addc_u32 s63, s63, 0
	v_mfma_f32_16x16x32_bf16 v[22:25], v[164:167], v[238:241], v[22:25]
	s_add_u32 s10, s48, 0xfffc0080
	v_mfma_f32_16x16x32_bf16 v[18:21], v[186:189], v[238:241], v[18:21]
	s_addc_u32 s11, s49, -1
	v_mfma_f32_16x16x32_bf16 v[62:65], v[168:171], v[218:221], v[62:65]
	s_add_i32 s69, 0, 0x10000
	v_mfma_f32_16x16x32_bf16 v[58:61], v[190:193], v[218:221], v[58:61]
	s_cmp_eq_u32 s68, 12
	v_mfma_f32_16x16x32_bf16 v[54:57], v[168:171], v[226:229], v[54:57]
	s_cselect_b32 s53, s43, s11
	v_mfma_f32_16x16x32_bf16 v[50:53], v[190:193], v[226:229], v[50:53]
	s_cselect_b32 s52, s57, s10
	v_mfma_f32_16x16x32_bf16 v[38:41], v[168:171], v[234:237], v[38:41]
	v_add_u32_e32 v130, s69, v161
	v_mfma_f32_16x16x32_bf16 v[34:37], v[190:193], v[234:237], v[34:37]
	s_cselect_b32 s51, s4, s63
	v_mfma_f32_16x16x32_bf16 v[22:25], v[168:171], v[242:245], v[22:25]
	s_cselect_b32 s50, s41, s62
	v_mfma_f32_16x16x32_bf16 v[18:21], v[190:193], v[242:245], v[18:21]
	s_add_i32 s81, 0, 0x14000
	v_mfma_f32_16x16x32_bf16 v[46:49], v[198:201], v[214:217], v[46:49]
	s_cmp_gt_u32 s68, 13
	v_mfma_f32_16x16x32_bf16 v[42:45], v[206:209], v[214:217], v[42:45]
	v_mfma_f32_16x16x32_bf16 v[30:33], v[198:201], v[222:225], v[30:33]
	v_mfma_f32_16x16x32_bf16 v[26:29], v[206:209], v[222:225], v[26:29]
	v_mfma_f32_16x16x32_bf16 v[14:17], v[198:201], v[230:233], v[14:17]
	v_mfma_f32_16x16x32_bf16 v[10:13], v[206:209], v[230:233], v[10:13]
	v_mfma_f32_16x16x32_bf16 v[6:9], v[198:201], v[238:241], v[6:9]
	v_mfma_f32_16x16x32_bf16 v[2:5], v[206:209], v[238:241], v[2:5]
	v_mfma_f32_16x16x32_bf16 v[46:49], v[202:205], v[218:221], v[46:49]
	v_mfma_f32_16x16x32_bf16 v[42:45], v[210:213], v[218:221], v[42:45]
	v_mfma_f32_16x16x32_bf16 v[30:33], v[202:205], v[226:229], v[30:33]
	v_mfma_f32_16x16x32_bf16 v[26:29], v[210:213], v[226:229], v[26:29]
	v_mfma_f32_16x16x32_bf16 v[14:17], v[202:205], v[234:237], v[14:17]
	v_mfma_f32_16x16x32_bf16 v[10:13], v[210:213], v[234:237], v[10:13]
	v_mfma_f32_16x16x32_bf16 v[6:9], v[202:205], v[242:245], v[6:9]
	v_mfma_f32_16x16x32_bf16 v[2:5], v[210:213], v[242:245], v[2:5]
	s_barrier
	s_cbranch_scc0 .Lgk_168
	s_and_b64 vcc, exec, s[20:21]
	s_mov_b64 s[62:63], s[14:15]
	s_cbranch_vccz .LBB0_171
	s_barrier

; #define PG8_STAGE(bufoff, gbase, voff) do { _Pragma("unroll") for (int _i = 0; _i < 2; ++_i) \
;         __builtin_amdgcn_global_load_lds((const unsigned*)((const char*)(gbase) + (voff)[_i]), (PG8_LAS unsigned*)(lds + (bufoff) + ldsw + _i * 8192), 16, 0, 0); } while (0)
; #define PG8_LDA(dst, b, h) do { _Pragma("unroll") for (int m = 0; m < 4; ++m) _Pragma("unroll") for (int k = 0; k < 2; ++k) dst[m][k] = *(const PG8_LAS bf16x8*)(lds + PG8_SA(b, h) + aoff + m * 2048 + k * 1024); } while (0)
; #define PG8_LDB(dst, b, h) do { _Pragma("unroll") for (int n = 0; n < 2; ++n) _Pragma("unroll") for (int k = 0; k < 2; ++k) dst[n][k] = *(const PG8_LAS bf16x8*)(lds + PG8_SB(b, h) + boff + n * 2048 + k * 1024); } while (0)
; #define PG8_MMA(ai, bj, At, Bt) do { __builtin_amdgcn_s_setprio(1); _Pragma("unroll") for (int m = 0; m < 4; ++m) _Pragma("unroll") for (int n = 0; n < 2; ++n) _Pragma("unroll") for (int k = 0; k < 2; ++k) \
;         acc[ai][bj][m][n] = __builtin_amdgcn_mfma_f32_16x16x32_bf16(Bt[n][k], At[m][k], acc[ai][bj][m][n], 0, 0, 0); __builtin_amdgcn_s_setprio(0); } while (0)
; #define PG8_WAIT_V(n) asm volatile("s_waitcnt vmcnt(" #n ")" ::: "memory")
; #define PG8_BAR __builtin_amdgcn_s_barrier()
; template <class Epi, class Sched, bool ALIGN_EPI = false, bool SP2 = false>
; __device__ __forceinline__ void gemm_phase(PG8_LAS unsigned char* lds, const Gemm g, const Sched& S, const Epi& E) {
;     ...
;         for (int t = 0; t < nt; t += 2) {
;             const bool last = (t == nt - 2);
;             const char* a1 = cA + (size_t)(t + 1) * kstep;
;             const char* a2 = last ? nA : cA + (size_t)(t + 2) * kstep; const char* b2 = last ? nB : cB + (size_t)(t + 2) * kstep;
;             const char* a3 = a2 + kstep; const char* b3 = b2 + kstep;
;             if (last && has_next) S.a_ready(nxt);
;             if constexpr (SP2) {
;             PG8_LDB(B0, 0, 0); PG8_LDB(B1, 0, 1); PG8_SCHED; PG8_LDA(At, 0, 0); PG8_STAGE(PG8_SA(1, 1), a1 + hstepA, voffA);
;             PG8_WAIT_V(8); PG8_WAIT_L(0); PG8_BAR; PG8_MMA(0, 0, At, B0); PG8_MMA(0, 1, At, B1); PG8_BAR; PG8_SCHED;
;             PG8_LDA(At, 0, 1); PG8_STAGE(PG8_SB(0, 0), b2, voffB); PG8_STAGE(PG8_SB(0, 1), b2 + hstepB, voffB); PG8_STAGE(PG8_SA(0, 0), a2, voffA);
;             PG8_WAIT_V(8); PG8_WAIT_L(0); PG8_BAR; PG8_MMA(1, 0, At, B0); PG8_MMA(1, 1, At, B1); PG8_BAR; PG8_SCHED;
.Lgk_726:
	ds_read_b128 v[160:163], v130
	ds_read_b128 v[170:173], v130 offset:1024
	ds_read_b128 v[186:189], v130 offset:2048
	ds_read_b128 v[190:193], v130 offset:3072
	v_add_u32_e32 v130, s13, v167
	ds_read_b128 v[198:201], v130
	ds_read_b128 v[202:205], v130 offset:1024
	ds_read_b128 v[206:209], v130 offset:2048
	ds_read_b128 v[210:213], v130 offset:3072
	v_lshl_add_u64 v[130:131], s[48:49], 0, v[156:157]
	s_add_i32 m0, s9, 0xc000
	ds_read_b128 v[214:217], v169
	ds_read_b128 v[218:221], v169 offset:1024
	ds_read_b128 v[222:225], v169 offset:2048
	ds_read_b128 v[226:229], v169 offset:3072
	ds_read_b128 v[230:233], v169 offset:4096
	ds_read_b128 v[234:237], v169 offset:5120
	ds_read_b128 v[238:241], v169 offset:6144
	ds_read_b128 v[242:245], v169 offset:7168
	global_load_lds_dwordx4 v[130:131], off
	v_lshl_add_u64 v[130:131], s[48:49], 0, v[158:159]
	s_add_i32 m0, s9, 0xe000
	s_nop 0
	global_load_lds_dwordx4 v[130:131], off
	s_waitcnt vmcnt(8)
	s_waitcnt lgkmcnt(0)
	s_barrier
	s_waitcnt lgkmcnt(0)
	v_mfma_f32_16x16x32_bf16 v[126:129], v[160:163], v[214:217], v[126:129]
	v_mfma_f32_16x16x32_bf16 v[122:125], v[186:189], v[214:217], v[122:125]
	v_mfma_f32_16x16x32_bf16 v[110:113], v[160:163], v[222:225], v[110:113]
	v_mfma_f32_16x16x32_bf16 v[106:109], v[186:189], v[222:225], v[106:109]
	v_mfma_f32_16x16x32_bf16 v[94:97], v[160:163], v[230:233], v[94:97]
	v_mfma_f32_16x16x32_bf16 v[90:93], v[186:189], v[230:233], v[90:93]
	v_mfma_f32_16x16x32_bf16 v[78:81], v[160:163], v[238:241], v[78:81]
	v_mfma_f32_16x16x32_bf16 v[74:77], v[186:189], v[238:241], v[74:77]
	v_mfma_f32_16x16x32_bf16 v[126:129], v[170:173], v[218:221], v[126:129]
	v_mfma_f32_16x16x32_bf16 v[122:125], v[190:193], v[218:221], v[122:125]
	v_mfma_f32_16x16x32_bf16 v[110:113], v[170:173], v[226:229], v[110:113]
	v_mfma_f32_16x16x32_bf16 v[106:109], v[190:193], v[226:229], v[106:109]
	v_mfma_f32_16x16x32_bf16 v[94:97], v[170:173], v[234:237], v[94:97]
	v_mfma_f32_16x16x32_bf16 v[90:93], v[190:193], v[234:237], v[90:93]
	v_mfma_f32_16x16x32_bf16 v[78:81], v[170:173], v[242:245], v[78:81]
	v_mfma_f32_16x16x32_bf16 v[74:77], v[190:193], v[242:245], v[74:77]
	v_mfma_f32_16x16x32_bf16 v[118:121], v[198:201], v[214:217], v[118:121]
	v_mfma_f32_16x16x32_bf16 v[114:117], v[206:209], v[214:217], v[114:117]
	v_mfma_f32_16x16x32_bf16 v[102:105], v[198:201], v[222:225], v[102:105]
	v_mfma_f32_16x16x32_bf16 v[98:101], v[206:209], v[222:225], v[98:101]
	v_mfma_f32_16x16x32_bf16 v[86:89], v[198:201], v[230:233], v[86:89]
	v_mfma_f32_16x16x32_bf16 v[82:85], v[206:209], v[230:233], v[82:85]
	v_mfma_f32_16x16x32_bf16 v[70:73], v[198:201], v[238:241], v[70:73]
	v_mfma_f32_16x16x32_bf16 v[66:69], v[206:209], v[238:241], v[66:69]
	v_mfma_f32_16x16x32_bf16 v[118:121], v[202:205], v[218:221], v[118:121]
	v_mfma_f32_16x16x32_bf16 v[114:117], v[210:213], v[218:221], v[114:117]
	v_mfma_f32_16x16x32_bf16 v[102:105], v[202:205], v[226:229], v[102:105]
	v_mfma_f32_16x16x32_bf16 v[98:101], v[210:213], v[226:229], v[98:101]
	v_mfma_f32_16x16x32_bf16 v[86:89], v[202:205], v[234:237], v[86:89]
	v_mfma_f32_16x16x32_bf16 v[82:85], v[210:213], v[234:237], v[82:85]
	v_mfma_f32_16x16x32_bf16 v[70:73], v[202:205], v[242:245], v[70:73]
	v_mfma_f32_16x16x32_bf16 v[66:69], v[210:213], v[242:245], v[66:69]
	s_barrier
	s_add_i32 s10, s12, s8
	v_lshl_add_u64 v[130:131], s[50:51], 0, v[0:1]
	s_mov_b32 m0, s10
	ds_read_b128 v[214:217], v169 offset:16384
	ds_read_b128 v[218:221], v169 offset:17408
	ds_read_b128 v[222:225], v169 offset:18432
	ds_read_b128 v[226:229], v169 offset:19456
	ds_read_b128 v[230:233], v169 offset:20480
	ds_read_b128 v[234:237], v169 offset:21504
	ds_read_b128 v[238:241], v169 offset:22528
	ds_read_b128 v[242:245], v169 offset:23552
	global_load_lds_dwordx4 v[130:131], off
	s_add_i32 m0, s10, 0x2000
	s_add_u32 s10, s50, 0x40000
	v_lshl_add_u64 v[132:133], s[50:51], 0, v[150:151]
	s_addc_u32 s11, s51, 0
	s_add_i32 s12, s13, s8
	global_load_lds_dwordx4 v[132:133], off
	v_lshl_add_u64 v[164:165], s[10:11], 0, v[0:1]
	s_mov_b32 m0, s12
	v_lshl_add_u64 v[246:247], s[52:53], 0, v[152:153]
	global_load_lds_dwordx4 v[164:165], off
	v_lshl_add_u64 v[164:165], s[10:11], 0, v[150:151]
	s_add_i32 m0, s12, 0x2000
	s_nop 0
	global_load_lds_dwordx4 v[164:165], off
	v_lshl_add_u64 v[164:165], s[52:53], 0, v[154:155]
	s_mov_b32 m0, s9
	s_nop 0
	global_load_lds_dwordx4 v[164:165], off
	s_mov_b32 m0, s30
	s_nop 0
	global_load_lds_dwordx4 v[246:247], off
	s_waitcnt vmcnt(8)
	s_waitcnt lgkmcnt(0)
	s_barrier
	s_waitcnt lgkmcnt(0)
	v_mfma_f32_16x16x32_bf16 v[62:65], v[160:163], v[214:217], v[62:65]
	v_mfma_f32_16x16x32_bf16 v[58:61], v[186:189], v[214:217], v[58:61]
	v_mfma_f32_16x16x32_bf16 v[46:49], v[160:163], v[222:225], v[46:49]
	v_mfma_f32_16x16x32_bf16 v[42:45], v[186:189], v[222:225], v[42:45]
	v_mfma_f32_16x16x32_bf16 v[30:33], v[160:163], v[230:233], v[30:33]
	v_mfma_f32_16x16x32_bf16 v[26:29], v[186:189], v[230:233], v[26:29]
	v_mfma_f32_16x16x32_bf16 v[14:17], v[160:163], v[238:241], v[14:17]
	v_mfma_f32_16x16x32_bf16 v[10:13], v[186:189], v[238:241], v[10:13]
	v_mfma_f32_16x16x32_bf16 v[62:65], v[170:173], v[218:221], v[62:65]
	v_mfma_f32_16x16x32_bf16 v[58:61], v[190:193], v[218:221], v[58:61]
	v_mfma_f32_16x16x32_bf16 v[46:49], v[170:173], v[226:229], v[46:49]
	v_mfma_f32_16x16x32_bf16 v[42:45], v[190:193], v[226:229], v[42:45]
	v_mfma_f32_16x16x32_bf16 v[30:33], v[170:173], v[234:237], v[30:33]
	v_mfma_f32_16x16x32_bf16 v[26:29], v[190:193], v[234:237], v[26:29]
	v_mfma_f32_16x16x32_bf16 v[14:17], v[170:173], v[242:245], v[14:17]
	v_mfma_f32_16x16x32_bf16 v[10:13], v[190:193], v[242:245], v[10:13]
	v_mfma_f32_16x16x32_bf16 v[54:57], v[198:201], v[214:217], v[54:57]
	v_mfma_f32_16x16x32_bf16 v[50:53], v[206:209], v[214:217], v[50:53]
	v_mfma_f32_16x16x32_bf16 v[38:41], v[198:201], v[222:225], v[38:41]
	v_mfma_f32_16x16x32_bf16 v[34:37], v[206:209], v[222:225], v[34:37]
	v_mfma_f32_16x16x32_bf16 v[22:25], v[198:201], v[230:233], v[22:25]
	v_mfma_f32_16x16x32_bf16 v[18:21], v[206:209], v[230:233], v[18:21]
	v_mfma_f32_16x16x32_bf16 v[6:9], v[198:201], v[238:241], v[6:9]
	v_mfma_f32_16x16x32_bf16 v[2:5], v[206:209], v[238:241], v[2:5]
	v_mfma_f32_16x16x32_bf16 v[54:57], v[202:205], v[218:221], v[54:57]
	v_mfma_f32_16x16x32_bf16 v[50:53], v[210:213], v[218:221], v[50:53]
	v_mfma_f32_16x16x32_bf16 v[38:41], v[202:205], v[226:229], v[38:41]
	v_mfma_f32_16x16x32_bf16 v[34:37], v[210:213], v[226:229], v[34:37]
	v_mfma_f32_16x16x32_bf16 v[22:25], v[202:205], v[234:237], v[22:25]
	v_mfma_f32_16x16x32_bf16 v[18:21], v[210:213], v[234:237], v[18:21]
	v_mfma_f32_16x16x32_bf16 v[6:9], v[202:205], v[242:245], v[6:9]
	v_mfma_f32_16x16x32_bf16 v[2:5], v[210:213], v[242:245], v[2:5]
	s_barrier
; #define PG8_STAGE(bufoff, gbase, voff) do { _Pragma("unroll") for (int _i = 0; _i < 2; ++_i) \
;         __builtin_amdgcn_global_load_lds((const unsigned*)((const char*)(gbase) + (voff)[_i]), (PG8_LAS unsigned*)(lds + (bufoff) + ldsw + _i * 8192), 16, 0, 0); } while (0)
; #define PG8_LDA(dst, b, h) do { _Pragma("unroll") for (int m = 0; m < 4; ++m) _Pragma("unroll") for (int k = 0; k < 2; ++k) dst[m][k] = *(const PG8_LAS bf16x8*)(lds + PG8_SA(b, h) + aoff + m * 2048 + k * 1024); } while (0)
; #define PG8_LDB(dst, b, h) do { _Pragma("unroll") for (int n = 0; n < 2; ++n) _Pragma("unroll") for (int k = 0; k < 2; ++k) dst[n][k] = *(const PG8_LAS bf16x8*)(lds + PG8_SB(b, h) + boff + n * 2048 + k * 1024); } while (0)
; #define PG8_MMA(ai, bj, At, Bt) do { __builtin_amdgcn_s_setprio(1); _Pragma("unroll") for (int m = 0; m < 4; ++m) _Pragma("unroll") for (int n = 0; n < 2; ++n) _Pragma("unroll") for (int k = 0; k < 2; ++k) \
;         acc[ai][bj][m][n] = __builtin_amdgcn_mfma_f32_16x16x32_bf16(Bt[n][k], At[m][k], acc[ai][bj][m][n], 0, 0, 0); __builtin_amdgcn_s_setprio(0); } while (0)
; #define PG8_WAIT_V(n) asm volatile("s_waitcnt vmcnt(" #n ")" ::: "memory")
; #define PG8_WAIT_L(n) asm volatile("s_waitcnt lgkmcnt(" #n ")" ::: "memory")
; #define PG8_BAR __builtin_amdgcn_s_barrier()
; #define PG8_SCHED __builtin_amdgcn_sched_barrier(0)
; template <class Epi, class Sched, bool ALIGN_EPI = false, bool SP2 = false>
; __device__ __forceinline__ void gemm_phase(PG8_LAS unsigned char* lds, const Gemm g, const Sched& S, const Epi& E) {
;     ...
;             PG8_LDB(B0, 1, 0); PG8_LDB(B1, 1, 1); PG8_SCHED; PG8_LDA(At, 1, 0); PG8_STAGE(PG8_SA(0, 1), a2 + hstepA, voffA);
;             PG8_WAIT_V(8); PG8_WAIT_L(0); PG8_BAR; PG8_MMA(0, 0, At, B0); PG8_MMA(0, 1, At, B1); PG8_BAR; PG8_SCHED;
	s_add_i32 s12, 0, 0x18000
	s_add_i32 s13, 0, 0x1c000
	v_add_u32_e32 v190, s12, v167
	v_add_u32_e32 v210, s13, v167
	ds_read_b128 v[160:163], v190
	ds_read_b128 v[170:173], v190 offset:1024
	ds_read_b128 v[186:189], v190 offset:2048
	ds_read_b128 v[190:193], v190 offset:3072
	ds_read_b128 v[198:201], v210
	ds_read_b128 v[202:205], v210 offset:1024
	ds_read_b128 v[206:209], v210 offset:2048
	ds_read_b128 v[210:213], v210 offset:3072
	s_add_u32 s10, s52, 0x40000
	s_addc_u32 s11, s53, 0
	s_mov_b32 m0, s31
	v_lshl_add_u64 v[248:249], s[10:11], 0, v[154:155]
	ds_read_b128 v[214:217], v169 offset:32768
	ds_read_b128 v[218:221], v169 offset:33792
	ds_read_b128 v[222:225], v169 offset:34816
	ds_read_b128 v[226:229], v169 offset:35840
	ds_read_b128 v[230:233], v169 offset:36864
	ds_read_b128 v[234:237], v169 offset:37888
	ds_read_b128 v[238:241], v169 offset:38912
	ds_read_b128 v[242:245], v169 offset:39936
	global_load_lds_dwordx4 v[248:249], off
	v_lshl_add_u64 v[248:249], s[10:11], 0, v[152:153]
	s_mov_b32 m0, s34
	s_nop 0
	global_load_lds_dwordx4 v[248:249], off
	s_waitcnt vmcnt(8)
	s_waitcnt lgkmcnt(0)
	s_barrier
	s_waitcnt lgkmcnt(0)
	v_mfma_f32_16x16x32_bf16 v[126:129], v[160:163], v[214:217], v[126:129]
	v_mfma_f32_16x16x32_bf16 v[122:125], v[186:189], v[214:217], v[122:125]
	v_mfma_f32_16x16x32_bf16 v[110:113], v[160:163], v[222:225], v[110:113]
	v_mfma_f32_16x16x32_bf16 v[106:109], v[186:189], v[222:225], v[106:109]
	v_mfma_f32_16x16x32_bf16 v[94:97], v[160:163], v[230:233], v[94:97]
	v_mfma_f32_16x16x32_bf16 v[90:93], v[186:189], v[230:233], v[90:93]
	v_mfma_f32_16x16x32_bf16 v[78:81], v[160:163], v[238:241], v[78:81]
	v_mfma_f32_16x16x32_bf16 v[74:77], v[186:189], v[238:241], v[74:77]
	v_mfma_f32_16x16x32_bf16 v[126:129], v[170:173], v[218:221], v[126:129]
	v_mfma_f32_16x16x32_bf16 v[122:125], v[190:193], v[218:221], v[122:125]
	v_mfma_f32_16x16x32_bf16 v[110:113], v[170:173], v[226:229], v[110:113]
	v_mfma_f32_16x16x32_bf16 v[106:109], v[190:193], v[226:229], v[106:109]
	v_mfma_f32_16x16x32_bf16 v[94:97], v[170:173], v[234:237], v[94:97]
	v_mfma_f32_16x16x32_bf16 v[90:93], v[190:193], v[234:237], v[90:93]
	v_mfma_f32_16x16x32_bf16 v[78:81], v[170:173], v[242:245], v[78:81]
	v_mfma_f32_16x16x32_bf16 v[74:77], v[190:193], v[242:245], v[74:77]
	v_mfma_f32_16x16x32_bf16 v[118:121], v[198:201], v[214:217], v[118:121]
	v_mfma_f32_16x16x32_bf16 v[114:117], v[206:209], v[214:217], v[114:117]
	v_mfma_f32_16x16x32_bf16 v[102:105], v[198:201], v[222:225], v[102:105]
	v_mfma_f32_16x16x32_bf16 v[98:101], v[206:209], v[222:225], v[98:101]
	v_mfma_f32_16x16x32_bf16 v[86:89], v[198:201], v[230:233], v[86:89]
	v_mfma_f32_16x16x32_bf16 v[82:85], v[206:209], v[230:233], v[82:85]
	v_mfma_f32_16x16x32_bf16 v[70:73], v[198:201], v[238:241], v[70:73]
	v_mfma_f32_16x16x32_bf16 v[66:69], v[206:209], v[238:241], v[66:69]
	v_mfma_f32_16x16x32_bf16 v[118:121], v[202:205], v[218:221], v[118:121]
	v_mfma_f32_16x16x32_bf16 v[114:117], v[210:213], v[218:221], v[114:117]
	v_mfma_f32_16x16x32_bf16 v[102:105], v[202:205], v[226:229], v[102:105]
	v_mfma_f32_16x16x32_bf16 v[98:101], v[210:213], v[226:229], v[98:101]
	v_mfma_f32_16x16x32_bf16 v[86:89], v[202:205], v[234:237], v[86:89]
	v_mfma_f32_16x16x32_bf16 v[82:85], v[210:213], v[234:237], v[82:85]
	v_mfma_f32_16x16x32_bf16 v[70:73], v[202:205], v[242:245], v[70:73]
	v_mfma_f32_16x16x32_bf16 v[66:69], v[210:213], v[242:245], v[66:69]
	s_barrier
; #define PG8_STAGE(bufoff, gbase, voff) do { _Pragma("unroll") for (int _i = 0; _i < 2; ++_i) \
;         __builtin_amdgcn_global_load_lds((const unsigned*)((const char*)(gbase) + (voff)[_i]), (PG8_LAS unsigned*)(lds + (bufoff) + ldsw + _i * 8192), 16, 0, 0); } while (0)
; #define PG8_LDA(dst, b, h) do { _Pragma("unroll") for (int m = 0; m < 4; ++m) _Pragma("unroll") for (int k = 0; k < 2; ++k) dst[m][k] = *(const PG8_LAS bf16x8*)(lds + PG8_SA(b, h) + aoff + m * 2048 + k * 1024); } while (0)
; #define PG8_MMA(ai, bj, At, Bt) do { __builtin_amdgcn_s_setprio(1); _Pragma("unroll") for (int m = 0; m < 4; ++m) _Pragma("unroll") for (int n = 0; n < 2; ++n) _Pragma("unroll") for (int k = 0; k < 2; ++k) \
;         acc[ai][bj][m][n] = __builtin_amdgcn_mfma_f32_16x16x32_bf16(Bt[n][k], At[m][k], acc[ai][bj][m][n], 0, 0, 0); __builtin_amdgcn_s_setprio(0); } while (0)
; #define PG8_WAIT_V(n) asm volatile("s_waitcnt vmcnt(" #n ")" ::: "memory")
; #define PG8_WAIT_L(n) asm volatile("s_waitcnt lgkmcnt(" #n ")" ::: "memory")
; #define PG8_BAR __builtin_amdgcn_s_barrier()
; #define PG8_SCHED __builtin_amdgcn_sched_barrier(0)
; template <class Epi, class Sched, bool ALIGN_EPI = false, bool SP2 = false>
; __device__ __forceinline__ void gemm_phase(PG8_LAS unsigned char* lds, const Gemm g, const Sched& S, const Epi& E) {
;     ...
;         for (int t = 0; t < nt; t += 2) {
;             const bool last = (t == nt - 2);
;             const char* a1 = cA + (size_t)(t + 1) * kstep;
;             const char* a2 = last ? nA : cA + (size_t)(t + 2) * kstep; const char* b2 = last ? nB : cB + (size_t)(t + 2) * kstep;
;             const char* a3 = a2 + kstep; const char* b3 = b2 + kstep;
;     ...
;             PG8_LDA(At, 1, 1); PG8_STAGE(PG8_SB(1, 0), b3, voffB); PG8_STAGE(PG8_SB(1, 1), b3 + hstepB, voffB); PG8_STAGE(PG8_SA(1, 0), a3, voffA);
;             PG8_WAIT_V(8); PG8_WAIT_L(0); PG8_BAR; PG8_MMA(1, 0, At, B0); PG8_MMA(1, 1, At, B1); PG8_BAR; PG8_SCHED;
	s_add_i32 s10, s12, s8
	v_lshl_add_u64 v[130:131], v[130:131], 0, s[2:3]
	s_mov_b32 m0, s10
	ds_read_b128 v[214:217], v169 offset:49152
	ds_read_b128 v[218:221], v169 offset:50176
	ds_read_b128 v[222:225], v169 offset:51200
	ds_read_b128 v[226:229], v169 offset:52224
	ds_read_b128 v[230:233], v169 offset:53248
	ds_read_b128 v[234:237], v169 offset:54272
	ds_read_b128 v[238:241], v169 offset:55296
	ds_read_b128 v[242:245], v169 offset:56320
	global_load_lds_dwordx4 v[130:131], off
	s_add_i32 m0, s10, 0x2000
	s_add_u32 s10, s50, 0x40080
	v_lshl_add_u64 v[130:131], v[132:133], 0, s[2:3]
	s_addc_u32 s11, s51, 0
	s_add_i32 s12, s13, s8
	global_load_lds_dwordx4 v[130:131], off
	v_lshl_add_u64 v[130:131], s[10:11], 0, v[0:1]
	s_mov_b32 m0, s12
	s_nop 0
	global_load_lds_dwordx4 v[130:131], off
	v_lshl_add_u64 v[130:131], s[10:11], 0, v[150:151]
	s_add_i32 m0, s12, 0x2000
	s_nop 0
	global_load_lds_dwordx4 v[130:131], off
	v_lshl_add_u64 v[130:131], v[164:165], 0, s[2:3]
	s_mov_b32 m0, s35
	s_nop 0
	global_load_lds_dwordx4 v[130:131], off
	v_lshl_add_u64 v[130:131], v[246:247], 0, s[2:3]
	s_mov_b32 m0, s54
	s_nop 0
	global_load_lds_dwordx4 v[130:131], off
	s_waitcnt vmcnt(8)
	s_waitcnt lgkmcnt(0)
	s_barrier
	s_waitcnt lgkmcnt(0)
	v_mfma_f32_16x16x32_bf16 v[62:65], v[160:163], v[214:217], v[62:65]
	v_mfma_f32_16x16x32_bf16 v[58:61], v[186:189], v[214:217], v[58:61]
	s_add_i32 s69, s69, 2
	v_mfma_f32_16x16x32_bf16 v[46:49], v[160:163], v[222:225], v[46:49]
	s_add_u32 s48, s48, 0x100
	v_mfma_f32_16x16x32_bf16 v[42:45], v[186:189], v[222:225], v[42:45]
	s_addc_u32 s49, s49, 0
	v_mfma_f32_16x16x32_bf16 v[30:33], v[160:163], v[230:233], v[30:33]
	s_add_u32 s63, s63, 0x100
	v_mfma_f32_16x16x32_bf16 v[26:29], v[186:189], v[230:233], v[26:29]
	s_addc_u32 s68, s68, 0
	v_mfma_f32_16x16x32_bf16 v[14:17], v[160:163], v[238:241], v[14:17]
	s_add_u32 s10, s48, 0xfffc0080
	v_mfma_f32_16x16x32_bf16 v[10:13], v[186:189], v[238:241], v[10:13]
	s_addc_u32 s11, s49, -1
	v_mfma_f32_16x16x32_bf16 v[62:65], v[170:173], v[218:221], v[62:65]
	s_add_i32 s12, 0, 0x10000
	v_mfma_f32_16x16x32_bf16 v[58:61], v[190:193], v[218:221], v[58:61]
	s_cmp_eq_u32 s69, 12
	v_mfma_f32_16x16x32_bf16 v[46:49], v[170:173], v[226:229], v[46:49]
	s_cselect_b32 s53, s43, s11
	v_mfma_f32_16x16x32_bf16 v[42:45], v[190:193], v[226:229], v[42:45]
	s_cselect_b32 s52, s62, s10
	v_mfma_f32_16x16x32_bf16 v[30:33], v[170:173], v[234:237], v[30:33]
	v_add_u32_e32 v130, s12, v167
	v_mfma_f32_16x16x32_bf16 v[26:29], v[190:193], v[234:237], v[26:29]
	s_cselect_b32 s51, s4, s68
	v_mfma_f32_16x16x32_bf16 v[14:17], v[170:173], v[242:245], v[14:17]
	s_cselect_b32 s50, s41, s63
	v_mfma_f32_16x16x32_bf16 v[10:13], v[190:193], v[242:245], v[10:13]
	s_add_i32 s13, 0, 0x14000
	v_mfma_f32_16x16x32_bf16 v[54:57], v[198:201], v[214:217], v[54:57]
	s_cmp_gt_u32 s69, 13
	v_mfma_f32_16x16x32_bf16 v[50:53], v[206:209], v[214:217], v[50:53]
	v_mfma_f32_16x16x32_bf16 v[38:41], v[198:201], v[222:225], v[38:41]
	v_mfma_f32_16x16x32_bf16 v[34:37], v[206:209], v[222:225], v[34:37]
	v_mfma_f32_16x16x32_bf16 v[22:25], v[198:201], v[230:233], v[22:25]
	v_mfma_f32_16x16x32_bf16 v[18:21], v[206:209], v[230:233], v[18:21]
	v_mfma_f32_16x16x32_bf16 v[6:9], v[198:201], v[238:241], v[6:9]
	v_mfma_f32_16x16x32_bf16 v[2:5], v[206:209], v[238:241], v[2:5]
	v_mfma_f32_16x16x32_bf16 v[54:57], v[202:205], v[218:221], v[54:57]
	v_mfma_f32_16x16x32_bf16 v[50:53], v[210:213], v[218:221], v[50:53]
	v_mfma_f32_16x16x32_bf16 v[38:41], v[202:205], v[226:229], v[38:41]
	v_mfma_f32_16x16x32_bf16 v[34:37], v[210:213], v[226:229], v[34:37]
	v_mfma_f32_16x16x32_bf16 v[22:25], v[202:205], v[234:237], v[22:25]
	v_mfma_f32_16x16x32_bf16 v[18:21], v[210:213], v[234:237], v[18:21]
	v_mfma_f32_16x16x32_bf16 v[6:9], v[202:205], v[242:245], v[6:9]
	v_mfma_f32_16x16x32_bf16 v[2:5], v[210:213], v[242:245], v[2:5]
	s_barrier
	s_cbranch_scc0 .Lgk_726
	s_and_b64 vcc, exec, s[20:21]
	s_mov_b64 s[62:63], s[14:15]
	s_cbranch_vccz .LBB0_729
	s_barrier

; #define PG8_STAGE(bufoff, gbase, voff) do { _Pragma("unroll") for (int _i = 0; _i < 2; ++_i) \
;         __builtin_amdgcn_global_load_lds((const unsigned*)((const char*)(gbase) + (voff)[_i]), (PG8_LAS unsigned*)(lds + (bufoff) + ldsw + _i * 8192), 16, 0, 0); } while (0)
; #define PG8_LDA(dst, b, h) do { _Pragma("unroll") for (int m = 0; m < 4; ++m) _Pragma("unroll") for (int k = 0; k < 2; ++k) dst[m][k] = *(const PG8_LAS bf16x8*)(lds + PG8_SA(b, h) + aoff + m * 2048 + k * 1024); } while (0)
; #define PG8_LDB(dst, b, h) do { _Pragma("unroll") for (int n = 0; n < 2; ++n) _Pragma("unroll") for (int k = 0; k < 2; ++k) dst[n][k] = *(const PG8_LAS bf16x8*)(lds + PG8_SB(b, h) + boff + n * 2048 + k * 1024); } while (0)
; #define PG8_MMA(ai, bj, At, Bt) do { __builtin_amdgcn_s_setprio(1); _Pragma("unroll") for (int m = 0; m < 4; ++m) _Pragma("unroll") for (int n = 0; n < 2; ++n) _Pragma("unroll") for (int k = 0; k < 2; ++k) \
;         acc[ai][bj][m][n] = __builtin_amdgcn_mfma_f32_16x16x32_bf16(Bt[n][k], At[m][k], acc[ai][bj][m][n], 0, 0, 0); __builtin_amdgcn_s_setprio(0); } while (0)
; #define PG8_WAIT_V(n) asm volatile("s_waitcnt vmcnt(" #n ")" ::: "memory")
; #define PG8_BAR __builtin_amdgcn_s_barrier()
; template <class Epi, class Sched, bool ALIGN_EPI = false, bool SP2 = false>
; __device__ __forceinline__ void gemm_phase(PG8_LAS unsigned char* lds, const Gemm g, const Sched& S, const Epi& E) {
;     ...
;         for (int t = 0; t < nt; t += 2) {
;             const bool last = (t == nt - 2);
;             const char* a1 = cA + (size_t)(t + 1) * kstep;
;             const char* a2 = last ? nA : cA + (size_t)(t + 2) * kstep; const char* b2 = last ? nB : cB + (size_t)(t + 2) * kstep;
;             const char* a3 = a2 + kstep; const char* b3 = b2 + kstep;
;             if (last && has_next) S.a_ready(nxt);
;             if constexpr (SP2) {
;             PG8_LDB(B0, 0, 0); PG8_LDB(B1, 0, 1); PG8_SCHED; PG8_LDA(At, 0, 0); PG8_STAGE(PG8_SA(1, 1), a1 + hstepA, voffA);
;             PG8_WAIT_V(8); PG8_WAIT_L(0); PG8_BAR; PG8_MMA(0, 0, At, B0); PG8_MMA(0, 1, At, B1); PG8_BAR; PG8_SCHED;
;             PG8_LDA(At, 0, 1); PG8_STAGE(PG8_SB(0, 0), b2, voffB); PG8_STAGE(PG8_SB(0, 1), b2 + hstepB, voffB); PG8_STAGE(PG8_SA(0, 0), a2, voffA);
;             PG8_WAIT_V(8); PG8_WAIT_L(0); PG8_BAR; PG8_MMA(1, 0, At, B0); PG8_MMA(1, 1, At, B1); PG8_BAR; PG8_SCHED;
.Lgk_856:
	ds_read_b128 v[164:167], v130
	ds_read_b128 v[168:171], v130 offset:1024
	ds_read_b128 v[186:189], v130 offset:2048
	ds_read_b128 v[190:193], v130 offset:3072
	v_add_u32_e32 v130, s13, v161
	ds_read_b128 v[198:201], v130
	ds_read_b128 v[202:205], v130 offset:1024
	ds_read_b128 v[206:209], v130 offset:2048
	ds_read_b128 v[210:213], v130 offset:3072
	v_lshl_add_u64 v[130:131], s[48:49], 0, v[156:157]
	s_add_i32 m0, s9, 0xc000
	ds_read_b128 v[214:217], v163
	ds_read_b128 v[218:221], v163 offset:1024
	ds_read_b128 v[222:225], v163 offset:2048
	ds_read_b128 v[226:229], v163 offset:3072
	ds_read_b128 v[230:233], v163 offset:4096
	ds_read_b128 v[234:237], v163 offset:5120
	ds_read_b128 v[238:241], v163 offset:6144
	ds_read_b128 v[242:245], v163 offset:7168
	global_load_lds_dwordx4 v[130:131], off
	v_lshl_add_u64 v[130:131], s[48:49], 0, v[158:159]
	s_add_i32 m0, s9, 0xe000
	s_nop 0
	global_load_lds_dwordx4 v[130:131], off
	s_waitcnt vmcnt(8)
	s_waitcnt lgkmcnt(0)
	s_barrier
	s_waitcnt lgkmcnt(0)
	v_mfma_f32_16x16x32_bf16 v[126:129], v[164:167], v[214:217], v[126:129]
	v_mfma_f32_16x16x32_bf16 v[122:125], v[186:189], v[214:217], v[122:125]
	v_mfma_f32_16x16x32_bf16 v[110:113], v[164:167], v[222:225], v[110:113]
	v_mfma_f32_16x16x32_bf16 v[106:109], v[186:189], v[222:225], v[106:109]
	v_mfma_f32_16x16x32_bf16 v[94:97], v[164:167], v[230:233], v[94:97]
	v_mfma_f32_16x16x32_bf16 v[90:93], v[186:189], v[230:233], v[90:93]
	v_mfma_f32_16x16x32_bf16 v[78:81], v[164:167], v[238:241], v[78:81]
	v_mfma_f32_16x16x32_bf16 v[74:77], v[186:189], v[238:241], v[74:77]
	v_mfma_f32_16x16x32_bf16 v[126:129], v[168:171], v[218:221], v[126:129]
	v_mfma_f32_16x16x32_bf16 v[122:125], v[190:193], v[218:221], v[122:125]
	v_mfma_f32_16x16x32_bf16 v[110:113], v[168:171], v[226:229], v[110:113]
	v_mfma_f32_16x16x32_bf16 v[106:109], v[190:193], v[226:229], v[106:109]
	v_mfma_f32_16x16x32_bf16 v[94:97], v[168:171], v[234:237], v[94:97]
	v_mfma_f32_16x16x32_bf16 v[90:93], v[190:193], v[234:237], v[90:93]
	v_mfma_f32_16x16x32_bf16 v[78:81], v[168:171], v[242:245], v[78:81]
	v_mfma_f32_16x16x32_bf16 v[74:77], v[190:193], v[242:245], v[74:77]
	v_mfma_f32_16x16x32_bf16 v[118:121], v[198:201], v[214:217], v[118:121]
	v_mfma_f32_16x16x32_bf16 v[114:117], v[206:209], v[214:217], v[114:117]
	v_mfma_f32_16x16x32_bf16 v[102:105], v[198:201], v[222:225], v[102:105]
	v_mfma_f32_16x16x32_bf16 v[98:101], v[206:209], v[222:225], v[98:101]
	v_mfma_f32_16x16x32_bf16 v[86:89], v[198:201], v[230:233], v[86:89]
	v_mfma_f32_16x16x32_bf16 v[82:85], v[206:209], v[230:233], v[82:85]
	v_mfma_f32_16x16x32_bf16 v[70:73], v[198:201], v[238:241], v[70:73]
	v_mfma_f32_16x16x32_bf16 v[66:69], v[206:209], v[238:241], v[66:69]
	v_mfma_f32_16x16x32_bf16 v[118:121], v[202:205], v[218:221], v[118:121]
	v_mfma_f32_16x16x32_bf16 v[114:117], v[210:213], v[218:221], v[114:117]
	v_mfma_f32_16x16x32_bf16 v[102:105], v[202:205], v[226:229], v[102:105]
	v_mfma_f32_16x16x32_bf16 v[98:101], v[210:213], v[226:229], v[98:101]
	v_mfma_f32_16x16x32_bf16 v[86:89], v[202:205], v[234:237], v[86:89]
	v_mfma_f32_16x16x32_bf16 v[82:85], v[210:213], v[234:237], v[82:85]
	v_mfma_f32_16x16x32_bf16 v[70:73], v[202:205], v[242:245], v[70:73]
	v_mfma_f32_16x16x32_bf16 v[66:69], v[210:213], v[242:245], v[66:69]
	s_barrier
	s_add_i32 s10, s12, s8
	v_lshl_add_u64 v[130:131], s[50:51], 0, v[0:1]
	s_mov_b32 m0, s10
	ds_read_b128 v[214:217], v163 offset:16384
	ds_read_b128 v[218:221], v163 offset:17408
	ds_read_b128 v[222:225], v163 offset:18432
	ds_read_b128 v[226:229], v163 offset:19456
	ds_read_b128 v[230:233], v163 offset:20480
	ds_read_b128 v[234:237], v163 offset:21504
	ds_read_b128 v[238:241], v163 offset:22528
	ds_read_b128 v[242:245], v163 offset:23552
	global_load_lds_dwordx4 v[130:131], off
	s_add_i32 m0, s10, 0x2000
	s_add_u32 s10, s50, 0x40000
	v_lshl_add_u64 v[132:133], s[50:51], 0, v[150:151]
	s_addc_u32 s11, s51, 0
	s_add_i32 s12, s13, s8
	global_load_lds_dwordx4 v[132:133], off
	v_lshl_add_u64 v[172:173], s[10:11], 0, v[0:1]
	s_mov_b32 m0, s12
	v_lshl_add_u64 v[246:247], s[52:53], 0, v[152:153]
	global_load_lds_dwordx4 v[172:173], off
	v_lshl_add_u64 v[172:173], s[10:11], 0, v[150:151]
	s_add_i32 m0, s12, 0x2000
	s_nop 0
	global_load_lds_dwordx4 v[172:173], off
	v_lshl_add_u64 v[172:173], s[52:53], 0, v[154:155]
	s_mov_b32 m0, s9
	s_nop 0
	global_load_lds_dwordx4 v[172:173], off
	s_mov_b32 m0, s30
	s_nop 0
	global_load_lds_dwordx4 v[246:247], off
	s_waitcnt vmcnt(8)
	s_waitcnt lgkmcnt(0)
	s_barrier
	s_waitcnt lgkmcnt(0)
	v_mfma_f32_16x16x32_bf16 v[62:65], v[164:167], v[214:217], v[62:65]
	v_mfma_f32_16x16x32_bf16 v[58:61], v[186:189], v[214:217], v[58:61]
	v_mfma_f32_16x16x32_bf16 v[46:49], v[164:167], v[222:225], v[46:49]
	v_mfma_f32_16x16x32_bf16 v[42:45], v[186:189], v[222:225], v[42:45]
	v_mfma_f32_16x16x32_bf16 v[30:33], v[164:167], v[230:233], v[30:33]
	v_mfma_f32_16x16x32_bf16 v[26:29], v[186:189], v[230:233], v[26:29]
	v_mfma_f32_16x16x32_bf16 v[14:17], v[164:167], v[238:241], v[14:17]
	v_mfma_f32_16x16x32_bf16 v[10:13], v[186:189], v[238:241], v[10:13]
	v_mfma_f32_16x16x32_bf16 v[62:65], v[168:171], v[218:221], v[62:65]
	v_mfma_f32_16x16x32_bf16 v[58:61], v[190:193], v[218:221], v[58:61]
	v_mfma_f32_16x16x32_bf16 v[46:49], v[168:171], v[226:229], v[46:49]
	v_mfma_f32_16x16x32_bf16 v[42:45], v[190:193], v[226:229], v[42:45]
	v_mfma_f32_16x16x32_bf16 v[30:33], v[168:171], v[234:237], v[30:33]
	v_mfma_f32_16x16x32_bf16 v[26:29], v[190:193], v[234:237], v[26:29]
	v_mfma_f32_16x16x32_bf16 v[14:17], v[168:171], v[242:245], v[14:17]
	v_mfma_f32_16x16x32_bf16 v[10:13], v[190:193], v[242:245], v[10:13]
	v_mfma_f32_16x16x32_bf16 v[54:57], v[198:201], v[214:217], v[54:57]
	v_mfma_f32_16x16x32_bf16 v[50:53], v[206:209], v[214:217], v[50:53]
	v_mfma_f32_16x16x32_bf16 v[38:41], v[198:201], v[222:225], v[38:41]
	v_mfma_f32_16x16x32_bf16 v[34:37], v[206:209], v[222:225], v[34:37]
	v_mfma_f32_16x16x32_bf16 v[22:25], v[198:201], v[230:233], v[22:25]
	v_mfma_f32_16x16x32_bf16 v[18:21], v[206:209], v[230:233], v[18:21]
	v_mfma_f32_16x16x32_bf16 v[6:9], v[198:201], v[238:241], v[6:9]
	v_mfma_f32_16x16x32_bf16 v[2:5], v[206:209], v[238:241], v[2:5]
	v_mfma_f32_16x16x32_bf16 v[54:57], v[202:205], v[218:221], v[54:57]
	v_mfma_f32_16x16x32_bf16 v[50:53], v[210:213], v[218:221], v[50:53]
	v_mfma_f32_16x16x32_bf16 v[38:41], v[202:205], v[226:229], v[38:41]
	v_mfma_f32_16x16x32_bf16 v[34:37], v[210:213], v[226:229], v[34:37]
	v_mfma_f32_16x16x32_bf16 v[22:25], v[202:205], v[234:237], v[22:25]
	v_mfma_f32_16x16x32_bf16 v[18:21], v[210:213], v[234:237], v[18:21]
	v_mfma_f32_16x16x32_bf16 v[6:9], v[202:205], v[242:245], v[6:9]
	v_mfma_f32_16x16x32_bf16 v[2:5], v[210:213], v[242:245], v[2:5]
	s_barrier
; #define PG8_STAGE(bufoff, gbase, voff) do { _Pragma("unroll") for (int _i = 0; _i < 2; ++_i) \
;         __builtin_amdgcn_global_load_lds((const unsigned*)((const char*)(gbase) + (voff)[_i]), (PG8_LAS unsigned*)(lds + (bufoff) + ldsw + _i * 8192), 16, 0, 0); } while (0)
; #define PG8_LDA(dst, b, h) do { _Pragma("unroll") for (int m = 0; m < 4; ++m) _Pragma("unroll") for (int k = 0; k < 2; ++k) dst[m][k] = *(const PG8_LAS bf16x8*)(lds + PG8_SA(b, h) + aoff + m * 2048 + k * 1024); } while (0)
; #define PG8_LDB(dst, b, h) do { _Pragma("unroll") for (int n = 0; n < 2; ++n) _Pragma("unroll") for (int k = 0; k < 2; ++k) dst[n][k] = *(const PG8_LAS bf16x8*)(lds + PG8_SB(b, h) + boff + n * 2048 + k * 1024); } while (0)
; #define PG8_MMA(ai, bj, At, Bt) do { __builtin_amdgcn_s_setprio(1); _Pragma("unroll") for (int m = 0; m < 4; ++m) _Pragma("unroll") for (int n = 0; n < 2; ++n) _Pragma("unroll") for (int k = 0; k < 2; ++k) \
;         acc[ai][bj][m][n] = __builtin_amdgcn_mfma_f32_16x16x32_bf16(Bt[n][k], At[m][k], acc[ai][bj][m][n], 0, 0, 0); __builtin_amdgcn_s_setprio(0); } while (0)
; #define PG8_WAIT_V(n) asm volatile("s_waitcnt vmcnt(" #n ")" ::: "memory")
; #define PG8_WAIT_L(n) asm volatile("s_waitcnt lgkmcnt(" #n ")" ::: "memory")
; #define PG8_BAR __builtin_amdgcn_s_barrier()
; #define PG8_SCHED __builtin_amdgcn_sched_barrier(0)
; template <class Epi, class Sched, bool ALIGN_EPI = false, bool SP2 = false>
; __device__ __forceinline__ void gemm_phase(PG8_LAS unsigned char* lds, const Gemm g, const Sched& S, const Epi& E) {
;     ...
;             PG8_LDB(B0, 1, 0); PG8_LDB(B1, 1, 1); PG8_SCHED; PG8_LDA(At, 1, 0); PG8_STAGE(PG8_SA(0, 1), a2 + hstepA, voffA);
;             PG8_WAIT_V(8); PG8_WAIT_L(0); PG8_BAR; PG8_MMA(0, 0, At, B0); PG8_MMA(0, 1, At, B1); PG8_BAR; PG8_SCHED;
	s_add_i32 s12, 0, 0x18000
	s_add_i32 s13, 0, 0x1c000
	v_add_u32_e32 v190, s12, v161
	v_add_u32_e32 v210, s13, v161
	ds_read_b128 v[164:167], v190
	ds_read_b128 v[168:171], v190 offset:1024
	ds_read_b128 v[186:189], v190 offset:2048
	ds_read_b128 v[190:193], v190 offset:3072
	ds_read_b128 v[198:201], v210
	ds_read_b128 v[202:205], v210 offset:1024
	ds_read_b128 v[206:209], v210 offset:2048
	ds_read_b128 v[210:213], v210 offset:3072
	s_add_u32 s10, s52, 0x40000
	s_addc_u32 s11, s53, 0
	s_mov_b32 m0, s31
	v_lshl_add_u64 v[248:249], s[10:11], 0, v[154:155]
	ds_read_b128 v[214:217], v163 offset:32768
	ds_read_b128 v[218:221], v163 offset:33792
	ds_read_b128 v[222:225], v163 offset:34816
	ds_read_b128 v[226:229], v163 offset:35840
	ds_read_b128 v[230:233], v163 offset:36864
	ds_read_b128 v[234:237], v163 offset:37888
	ds_read_b128 v[238:241], v163 offset:38912
	ds_read_b128 v[242:245], v163 offset:39936
	global_load_lds_dwordx4 v[248:249], off
	v_lshl_add_u64 v[248:249], s[10:11], 0, v[152:153]
	s_mov_b32 m0, s34
	s_nop 0
	global_load_lds_dwordx4 v[248:249], off
	s_waitcnt vmcnt(8)
	s_waitcnt lgkmcnt(0)
	s_barrier
	s_waitcnt lgkmcnt(0)
	v_mfma_f32_16x16x32_bf16 v[126:129], v[164:167], v[214:217], v[126:129]
	v_mfma_f32_16x16x32_bf16 v[122:125], v[186:189], v[214:217], v[122:125]
	v_mfma_f32_16x16x32_bf16 v[110:113], v[164:167], v[222:225], v[110:113]
	v_mfma_f32_16x16x32_bf16 v[106:109], v[186:189], v[222:225], v[106:109]
	v_mfma_f32_16x16x32_bf16 v[94:97], v[164:167], v[230:233], v[94:97]
	v_mfma_f32_16x16x32_bf16 v[90:93], v[186:189], v[230:233], v[90:93]
	v_mfma_f32_16x16x32_bf16 v[78:81], v[164:167], v[238:241], v[78:81]
	v_mfma_f32_16x16x32_bf16 v[74:77], v[186:189], v[238:241], v[74:77]
	v_mfma_f32_16x16x32_bf16 v[126:129], v[168:171], v[218:221], v[126:129]
	v_mfma_f32_16x16x32_bf16 v[122:125], v[190:193], v[218:221], v[122:125]
	v_mfma_f32_16x16x32_bf16 v[110:113], v[168:171], v[226:229], v[110:113]
	v_mfma_f32_16x16x32_bf16 v[106:109], v[190:193], v[226:229], v[106:109]
	v_mfma_f32_16x16x32_bf16 v[94:97], v[168:171], v[234:237], v[94:97]
	v_mfma_f32_16x16x32_bf16 v[90:93], v[190:193], v[234:237], v[90:93]
	v_mfma_f32_16x16x32_bf16 v[78:81], v[168:171], v[242:245], v[78:81]
	v_mfma_f32_16x16x32_bf16 v[74:77], v[190:193], v[242:245], v[74:77]
	v_mfma_f32_16x16x32_bf16 v[118:121], v[198:201], v[214:217], v[118:121]
	v_mfma_f32_16x16x32_bf16 v[114:117], v[206:209], v[214:217], v[114:117]
	v_mfma_f32_16x16x32_bf16 v[102:105], v[198:201], v[222:225], v[102:105]
	v_mfma_f32_16x16x32_bf16 v[98:101], v[206:209], v[222:225], v[98:101]
	v_mfma_f32_16x16x32_bf16 v[86:89], v[198:201], v[230:233], v[86:89]
	v_mfma_f32_16x16x32_bf16 v[82:85], v[206:209], v[230:233], v[82:85]
	v_mfma_f32_16x16x32_bf16 v[70:73], v[198:201], v[238:241], v[70:73]
	v_mfma_f32_16x16x32_bf16 v[66:69], v[206:209], v[238:241], v[66:69]
	v_mfma_f32_16x16x32_bf16 v[118:121], v[202:205], v[218:221], v[118:121]
	v_mfma_f32_16x16x32_bf16 v[114:117], v[210:213], v[218:221], v[114:117]
	v_mfma_f32_16x16x32_bf16 v[102:105], v[202:205], v[226:229], v[102:105]
	v_mfma_f32_16x16x32_bf16 v[98:101], v[210:213], v[226:229], v[98:101]
	v_mfma_f32_16x16x32_bf16 v[86:89], v[202:205], v[234:237], v[86:89]
	v_mfma_f32_16x16x32_bf16 v[82:85], v[210:213], v[234:237], v[82:85]
	v_mfma_f32_16x16x32_bf16 v[70:73], v[202:205], v[242:245], v[70:73]
	v_mfma_f32_16x16x32_bf16 v[66:69], v[210:213], v[242:245], v[66:69]
	s_barrier
; #define PG8_STAGE(bufoff, gbase, voff) do { _Pragma("unroll") for (int _i = 0; _i < 2; ++_i) \
;         __builtin_amdgcn_global_load_lds((const unsigned*)((const char*)(gbase) + (voff)[_i]), (PG8_LAS unsigned*)(lds + (bufoff) + ldsw + _i * 8192), 16, 0, 0); } while (0)
; #define PG8_LDA(dst, b, h) do { _Pragma("unroll") for (int m = 0; m < 4; ++m) _Pragma("unroll") for (int k = 0; k < 2; ++k) dst[m][k] = *(const PG8_LAS bf16x8*)(lds + PG8_SA(b, h) + aoff + m * 2048 + k * 1024); } while (0)
; #define PG8_MMA(ai, bj, At, Bt) do { __builtin_amdgcn_s_setprio(1); _Pragma("unroll") for (int m = 0; m < 4; ++m) _Pragma("unroll") for (int n = 0; n < 2; ++n) _Pragma("unroll") for (int k = 0; k < 2; ++k) \
;         acc[ai][bj][m][n] = __builtin_amdgcn_mfma_f32_16x16x32_bf16(Bt[n][k], At[m][k], acc[ai][bj][m][n], 0, 0, 0); __builtin_amdgcn_s_setprio(0); } while (0)
; #define PG8_WAIT_V(n) asm volatile("s_waitcnt vmcnt(" #n ")" ::: "memory")
; #define PG8_WAIT_L(n) asm volatile("s_waitcnt lgkmcnt(" #n ")" ::: "memory")
; #define PG8_BAR __builtin_amdgcn_s_barrier()
; #define PG8_SCHED __builtin_amdgcn_sched_barrier(0)
; template <class Epi, class Sched, bool ALIGN_EPI = false, bool SP2 = false>
; __device__ __forceinline__ void gemm_phase(PG8_LAS unsigned char* lds, const Gemm g, const Sched& S, const Epi& E) {
;     ...
;         for (int t = 0; t < nt; t += 2) {
;             const bool last = (t == nt - 2);
;             const char* a1 = cA + (size_t)(t + 1) * kstep;
;             const char* a2 = last ? nA : cA + (size_t)(t + 2) * kstep; const char* b2 = last ? nB : cB + (size_t)(t + 2) * kstep;
;             const char* a3 = a2 + kstep; const char* b3 = b2 + kstep;
;     ...
;             PG8_LDA(At, 1, 1); PG8_STAGE(PG8_SB(1, 0), b3, voffB); PG8_STAGE(PG8_SB(1, 1), b3 + hstepB, voffB); PG8_STAGE(PG8_SA(1, 0), a3, voffA);
;             PG8_WAIT_V(8); PG8_WAIT_L(0); PG8_BAR; PG8_MMA(1, 0, At, B0); PG8_MMA(1, 1, At, B1); PG8_BAR; PG8_SCHED;
	s_add_i32 s10, s12, s8
	v_lshl_add_u64 v[130:131], v[130:131], 0, s[2:3]
	s_mov_b32 m0, s10
	ds_read_b128 v[214:217], v163 offset:49152
	ds_read_b128 v[218:221], v163 offset:50176
	ds_read_b128 v[222:225], v163 offset:51200
	ds_read_b128 v[226:229], v163 offset:52224
	ds_read_b128 v[230:233], v163 offset:53248
	ds_read_b128 v[234:237], v163 offset:54272
	ds_read_b128 v[238:241], v163 offset:55296
	ds_read_b128 v[242:245], v163 offset:56320
	global_load_lds_dwordx4 v[130:131], off
	s_add_i32 m0, s10, 0x2000
	s_add_u32 s10, s50, 0x40080
	v_lshl_add_u64 v[130:131], v[132:133], 0, s[2:3]
	s_addc_u32 s11, s51, 0
	s_add_i32 s12, s13, s8
	global_load_lds_dwordx4 v[130:131], off
	v_lshl_add_u64 v[130:131], s[10:11], 0, v[0:1]
	s_mov_b32 m0, s12
	s_nop 0
	global_load_lds_dwordx4 v[130:131], off
	v_lshl_add_u64 v[130:131], s[10:11], 0, v[150:151]
	s_add_i32 m0, s12, 0x2000
	s_nop 0
	global_load_lds_dwordx4 v[130:131], off
	v_lshl_add_u64 v[130:131], v[172:173], 0, s[2:3]
	s_mov_b32 m0, s35
	s_nop 0
	global_load_lds_dwordx4 v[130:131], off
	v_lshl_add_u64 v[130:131], v[246:247], 0, s[2:3]
	s_mov_b32 m0, s54
	s_nop 0
	global_load_lds_dwordx4 v[130:131], off
	s_waitcnt vmcnt(8)
	s_waitcnt lgkmcnt(0)
	s_barrier
	s_waitcnt lgkmcnt(0)
	v_mfma_f32_16x16x32_bf16 v[62:65], v[164:167], v[214:217], v[62:65]
	v_mfma_f32_16x16x32_bf16 v[58:61], v[186:189], v[214:217], v[58:61]
	s_add_i32 s69, s69, 2
	v_mfma_f32_16x16x32_bf16 v[46:49], v[164:167], v[222:225], v[46:49]
	s_add_u32 s48, s48, 0x100
	v_mfma_f32_16x16x32_bf16 v[42:45], v[186:189], v[222:225], v[42:45]
	s_addc_u32 s49, s49, 0
	v_mfma_f32_16x16x32_bf16 v[30:33], v[164:167], v[230:233], v[30:33]
	s_add_u32 s63, s63, 0x100
	v_mfma_f32_16x16x32_bf16 v[26:29], v[186:189], v[230:233], v[26:29]
	s_addc_u32 s68, s68, 0
	v_mfma_f32_16x16x32_bf16 v[14:17], v[164:167], v[238:241], v[14:17]
	s_add_u32 s10, s48, 0xfffc0080
	v_mfma_f32_16x16x32_bf16 v[10:13], v[186:189], v[238:241], v[10:13]
	s_addc_u32 s11, s49, -1
	v_mfma_f32_16x16x32_bf16 v[62:65], v[168:171], v[218:221], v[62:65]
	s_add_i32 s12, 0, 0x10000
	v_mfma_f32_16x16x32_bf16 v[58:61], v[190:193], v[218:221], v[58:61]
	s_cmp_eq_u32 s69, 12
	v_mfma_f32_16x16x32_bf16 v[46:49], v[168:171], v[226:229], v[46:49]
	s_cselect_b32 s53, s43, s11
	v_mfma_f32_16x16x32_bf16 v[42:45], v[190:193], v[226:229], v[42:45]
	s_cselect_b32 s52, s62, s10
	v_mfma_f32_16x16x32_bf16 v[30:33], v[168:171], v[234:237], v[30:33]
	v_add_u32_e32 v130, s12, v161
	v_mfma_f32_16x16x32_bf16 v[26:29], v[190:193], v[234:237], v[26:29]
	s_cselect_b32 s51, s4, s68
	v_mfma_f32_16x16x32_bf16 v[14:17], v[168:171], v[242:245], v[14:17]
	s_cselect_b32 s50, s41, s63
	v_mfma_f32_16x16x32_bf16 v[10:13], v[190:193], v[242:245], v[10:13]
	s_add_i32 s13, 0, 0x14000
	v_mfma_f32_16x16x32_bf16 v[54:57], v[198:201], v[214:217], v[54:57]
	s_cmp_gt_u32 s69, 13
	v_mfma_f32_16x16x32_bf16 v[50:53], v[206:209], v[214:217], v[50:53]
	v_mfma_f32_16x16x32_bf16 v[38:41], v[198:201], v[222:225], v[38:41]
	v_mfma_f32_16x16x32_bf16 v[34:37], v[206:209], v[222:225], v[34:37]
	v_mfma_f32_16x16x32_bf16 v[22:25], v[198:201], v[230:233], v[22:25]
	v_mfma_f32_16x16x32_bf16 v[18:21], v[206:209], v[230:233], v[18:21]
	v_mfma_f32_16x16x32_bf16 v[6:9], v[198:201], v[238:241], v[6:9]
	v_mfma_f32_16x16x32_bf16 v[2:5], v[206:209], v[238:241], v[2:5]
	v_mfma_f32_16x16x32_bf16 v[54:57], v[202:205], v[218:221], v[54:57]
	v_mfma_f32_16x16x32_bf16 v[50:53], v[210:213], v[218:221], v[50:53]
	v_mfma_f32_16x16x32_bf16 v[38:41], v[202:205], v[226:229], v[38:41]
	v_mfma_f32_16x16x32_bf16 v[34:37], v[210:213], v[226:229], v[34:37]
	v_mfma_f32_16x16x32_bf16 v[22:25], v[202:205], v[234:237], v[22:25]
	v_mfma_f32_16x16x32_bf16 v[18:21], v[210:213], v[234:237], v[18:21]
	v_mfma_f32_16x16x32_bf16 v[6:9], v[202:205], v[242:245], v[6:9]
	v_mfma_f32_16x16x32_bf16 v[2:5], v[210:213], v[242:245], v[2:5]
	s_barrier
	s_cbranch_scc0 .Lgk_856
	s_and_b64 vcc, exec, s[20:21]
	s_mov_b64 s[62:63], s[14:15]
	s_cbranch_vccz .LBB0_859
	s_barrier
